# P9 walks its four output tiles in reverse order so its first reads hit the rows P8 wrote last (memory-side cache)
# speedup vs baseline: 1.0078x; 1.0013x over previous
;     __host__ __device__ bool next(int i, Unit& u) const {
;         const long L = (long)i * G + c; if (L >= nwg) return false;
;         int wgid = (int)L; { const int q = nwg / NXCD, r = nwg % NXCD, xcd = wgid % NXCD, off = wgid / NXCD; wgid = (xcd < r ? xcd * (q + 1) : r * (q + 1) + (xcd - r) * q) + off; }
;         const int nig = WGM * nN, gid = wgid / nig, fm = gid * WGM, gsz = (nM - fm) < WGM ? (nM - fm) : WGM;
;         u.pm = fm + ((wgid % nig) % gsz); u.pn = (wgid % nig) / gsz; return true;
; __global__ void __launch_bounds__(512, 2) hymba_fwd(Args a) {
;     ...
;     if (IN(9)) {
;         Epi<4> E{RB, DM, nullptr, nullptr, PSQ, nullptr, nullptr, nullptr};
;         run_gemm<4>(lds, RA, WDN_T, NTOK, DM, DFF, DFF, 128, 0, bx, E);
.LBB0_1705:
	s_add_i32 s95, s2, 0x300
	v_readlane_b32 s6, v247, 3
	v_readlane_b32 s7, v247, 4
	s_cmp_lt_i32 s6, 10
	s_cselect_b64 s[6:7], -1, 0
	s_and_b64 s[8:9], s[6:7], s[4:5]
	s_andn2_b64 vcc, exec, s[8:9]
	s_cbranch_vccnz .LBB0_1748
	s_cmpk_lt_i32 s95, 0x400
	s_cselect_b64 s[4:5], -1, 0
	s_cmpk_gt_i32 s95, 0x3ff
	v_readfirstlane_b32 s16, v156
	s_cbranch_scc1 .LBB0_1712
	s_ashr_i32 s3, s95, 31
	s_lshr_b32 s3, s3, 29
	s_add_i32 s3, s95, s3
	s_and_b32 s6, s3, -8
	s_sub_i32 s10, s95, s6
	s_cmp_gt_i32 s10, -1
	s_cbranch_scc0 .LBB0_1709
	s_lshl_b32 s11, s10, 7
	s_cbranch_execz .LBB0_1710
	s_branch .LBB0_1711

;     __host__ __device__ bool next(int i, Unit& u) const {
;         const long L = (long)i * G + c; if (L >= nwg) return false;
;         int wgid = (int)L; { const int q = nwg / NXCD, r = nwg % NXCD, xcd = wgid % NXCD, off = wgid / NXCD; wgid = (xcd < r ? xcd * (q + 1) : r * (q + 1) + (xcd - r) * q) + off; }
;         const int nig = WGM * nN, gid = wgid / nig, fm = gid * WGM, gsz = (nM - fm) < WGM ? (nM - fm) : WGM;
;         u.pm = fm + ((wgid % nig) % gsz); u.pn = (wgid % nig) / gsz; return true;
; template <class Epi, class Sched, bool ALIGN_EPI = true, bool SP2 = true>
; __device__ __forceinline__ void gemm_phase(LAS unsigned char* lds, const Gemm g, const Sched& S, const Epi& E) {
;     ...
;         const bool has_next = S.next(ui + 1, nxt);
.LBB0_1718:
	s_add_i32 s53, s53, 1
	s_mul_i32 s6, s53, s44
	s_mul_hi_u32 s7, s53, s45
	s_add_i32 s7, s7, s6
	s_mul_i32 s6, s53, s45
	s_sub_u32 s22, s95, s6
	s_mov_b32 s23, 0
	v_cmp_gt_i64_e32 vcc, s[22:23], v[142:143]
	v_cmp_lt_i64_e64 s[6:7], s[22:23], v[140:141]
	s_cbranch_vccnz .LBB0_1724
	s_ashr_i32 s18, s22, 31
	s_lshr_b32 s18, s18, 29
	s_add_i32 s20, s22, s18
	s_and_b32 s18, s20, -8
	s_sub_i32 s21, s22, s18
	s_cmp_gt_i32 s21, -1
	s_mov_b64 s[18:19], -1
	s_cbranch_scc0 .LBB0_1721
	s_lshl_b32 s22, s21, 7
	s_mov_b64 s[18:19], 0
